# prologue item order: weight transposes before the XN rows (phase tail is the fine-grained HBM-bound XN items); plus cache_tail 16-byte image stores
# baseline (speedup 1.0000x reference)
.LBB0_23:
	s_or_b64 exec, exec, s[4:5]
	s_cmpk_lt_i32 s40, 0x100
	s_cbranch_scc1 .Lp0_norot
	s_add_i32 s40, s40, 0x2100
	s_cmpk_lt_i32 s40, 0x3080
	s_cbranch_scc1 .Lp0_norot
	s_sub_i32 s40, s40, 0x2f80
.Lp0_norot:
	s_cmpk_gt_i32 s40, 0xff
	s_mov_b64 s[4:5], -1
	s_cbranch_scc0 .LBB0_49
	s_cmpk_gt_u32 s40, 0x21ff
	s_cbranch_scc0 .LBB0_46
	s_cmpk_gt_u32 s40, 0x287f
	s_cbranch_scc0 .LBB0_41
	s_cmpk_gt_u32 s40, 0x2a7f
	s_cbranch_scc0 .LBB0_36
	s_load_dwordx2 s[4:5], s[8:9], 0xc0
	s_cmpk_gt_u32 s40, 0x2e7f
	s_mov_b64 s[6:7], -1
	s_cbranch_scc0 .LBB0_31
	s_load_dwordx2 s[42:43], s[8:9], 0xb0
	s_lshl_b32 s6, s40, 1
	s_lshl_b32 s10, s40, 5
	s_and_b32 s6, s6, 0x7fc0
	s_and_b32 s10, s10, 0x3e0
	s_add_i32 s6, s6, 0xa300
	s_lshl_b32 s44, s10, 2
	s_waitcnt lgkmcnt(0)
	s_add_u32 s42, s42, s44
	v_lshlrev_b32_e32 v1, 2, v88
	s_addc_u32 s43, s43, 0
	v_and_b32_e32 v62, 0x7c, v1
	v_ashrrev_i32_e32 v22, 5, v88
	v_lshl_add_u64 v[18:19], s[42:43], 0, v[62:63]
	s_and_b32 s42, s6, 0xffc0
	v_add_u32_e32 v26, 4, v22
	v_add_u32_e32 v30, 8, v22
	v_add_u32_e32 v34, 12, v22
	v_add_u32_e32 v38, 16, v22
	v_add_u32_e32 v42, 20, v22
	v_add_u32_e32 v46, 24, v22
	v_add_u32_e32 v50, 28, v22
	v_add_u32_e32 v24, s42, v22
	v_add_u32_e32 v28, s42, v26
	v_add_u32_e32 v32, s42, v30
	v_add_u32_e32 v36, s42, v34
	v_add_u32_e32 v40, s42, v38
	v_add_u32_e32 v44, s42, v42
	v_add_u32_e32 v48, s42, v46
	v_add_u32_e32 v52, s42, v50
	s_mov_b32 s7, 1
	v_add_u32_e32 v20, s62, v62
	v_mov_b32_e32 v1, v22
	v_mov_b32_e32 v21, v24
	v_mov_b32_e32 v23, v26
	v_mov_b32_e32 v25, v28
	v_mov_b32_e32 v27, v30
	v_mov_b32_e32 v29, v32
	v_mov_b32_e32 v31, v34
	v_mov_b32_e32 v33, v36
	v_mov_b32_e32 v35, v38
	v_mov_b32_e32 v37, v40
	v_mov_b32_e32 v39, v42
	v_mov_b32_e32 v41, v44
	v_mov_b32_e32 v43, v46
	v_mov_b32_e32 v45, v48
	v_mov_b32_e32 v47, v50
	v_mov_b32_e32 v49, v52
	s_mov_b32 s42, 0
	s_mov_b32 s43, 32
